# lora: weights re-laid in MFMA-fragment order by the workgroups idle in phase 4's last round, so each weight load is one contiguous 1 KiB per wave; left-over items one n-tile per wave
# speedup vs baseline: 1.0120x; 1.0070x over previous
; __device__ __forceinline__ void phase_lora(const Ctx& p, LAS unsigned char* lds) {
;     ...
;         auto ldw = [&](WF& f, int nt) {
;             const int n = nt * 16 + q, c = nt * 16 + 4 * g;
; #pragma unroll
;             for (int ks = 0; ks < 2; ++ks) { f.w[ks] = *(const bf16x8*)(w2T + n * 64 + ks * 32 + 8 * g); f.a[ks] = *(const bf16x8*)(a2T + n * 64 + ks * 32 + 8 * g); }
; #pragma unroll
;             for (int ks = 0; ks < 4; ++ks) f.gq[ks] = *(const bf16x8*)(g2T + n * 128 + ks * 32 + 8 * g);
.LBB0_815:
	s_waitcnt vmcnt(0)
	v_readlane_b32 s74, v238, 5
	v_readlane_b32 s75, v238, 6
	v_readlane_b32 s73, v238, 4
	s_barrier
	s_cmpk_lt_u32 s28, 0x55
	s_cbranch_scc1 .Llws_done
	s_sub_u32 s2, s28, 0x55
	s_lshl_b32 s2, s2, 9
	v_add_u32_e32 v0, s2, v180
	v_cmp_gt_u32_e32 vcc, 0x4000, v0
	s_and_saveexec_b64 s[4:5], vcc
	s_cbranch_execz .Llws_skip
	v_and_b32_e32 v2, 15, v0
	v_bfe_u32 v3, v0, 4, 2
	v_lshlrev_b32_e32 v3, 4, v3
	v_lshrrev_b32_e32 v4, 12, v0
	v_lshlrev_b32_e32 v4, 16, v4
	v_bfe_u32 v5, v0, 7, 5
	v_lshl_or_b32 v4, v5, 11, v4
	v_lshl_or_b32 v4, v2, 7, v4
	v_bfe_u32 v5, v0, 6, 1
	v_lshl_or_b32 v4, v5, 6, v4
	v_or_b32_e32 v4, v4, v3
	v_subrev_u32_e32 v6, 0x2000, v0
	v_lshrrev_b32_e32 v7, 8, v6
	v_lshlrev_b32_e32 v7, 12, v7
	v_lshl_or_b32 v7, v2, 8, v7
	v_bfe_u32 v5, v6, 6, 2
	v_lshl_or_b32 v7, v5, 6, v7
	v_or_b32_e32 v7, v7, v3
	v_add_u32_e32 v7, 0x20000, v7
	v_cmp_gt_u32_e32 vcc, 0x2000, v0
	s_nop 1
	v_cndmask_b32_e32 v4, v7, v4, vcc
	v_lshlrev_b32_e32 v1, 4, v0
	s_add_u32 s6, s30, 0x3110000
	s_addc_u32 s7, s31, 0
	s_add_u32 s8, s30, 0x3190000
	s_addc_u32 s9, s31, 0
	global_load_dwordx4 v[8:11], v4, s[6:7]
	s_waitcnt vmcnt(0)
	global_store_dwordx4 v1, v[8:11], s[8:9]

; __device__ __forceinline__ unsigned xb_ld(unsigned* p)              { return __hip_atomic_load(p, __ATOMIC_RELAXED, __HIP_MEMORY_SCOPE_AGENT); }
; __device__ __forceinline__ void xcd_barrier_complete(unsigned* bar, unsigned x, unsigned& nloc, unsigned& nx) {
;     const unsigned G = gridDim.x * gridDim.y * gridDim.z;
;     unsigned sum, cnt, mine, sp = 0u;
;     for (;;) {
;         sum = 0u; cnt = 0u; mine = 0u;
; #pragma unroll
;         for (unsigned j = 0; j < 16; ++j) { const unsigned c = xb_ld(&bar[XB_XCNT(j)]); sum += c; cnt += (c > 0u) ? 1u : 0u; mine = (j == x) ? c : mine; }
; __device__ __forceinline__ void xcd_barrier(const XcdBarrier& b) {
;     asm volatile("s_waitcnt vmcnt(0)" ::: "memory");
;     __syncthreads();
;     if (threadIdx.x == 0) {
;         unsigned* bar = b.bar;
;         __builtin_amdgcn_s_waitcnt(0);
;         unsigned nloc = b.st[0], nx = b.st[1];
;         if (nloc == 0u) { xcd_barrier_complete(bar, b.x, nloc, nx); b.st[0] = nloc; b.st[1] = nx; }
.Llws_done:
.LBB0_816:
	s_cmp_gt_i32 s37, 5
	v_readlane_b32 s0, v238, 2
	s_cselect_b64 s[2:3], -1, 0
	v_readlane_b32 s1, v238, 3
	s_and_b64 s[4:5], s[0:1], s[2:3]
	s_andn2_b64 vcc, exec, s[4:5]
	s_cbranch_vccnz .LBB0_870
	s_waitcnt vmcnt(0)
	v_readlane_b32 s0, v238, 0
	v_readlane_b32 s1, v238, 1
	s_waitcnt vmcnt(0) lgkmcnt(0)
	s_barrier
	s_and_saveexec_b64 s[4:5], s[0:1]
	s_cbranch_execz .LBB0_869
	s_add_i32 s6, 0, 0x23800
	v_mov_b32_e32 v0, s6
	s_waitcnt vmcnt(0) expcnt(0) lgkmcnt(0)
	ds_read_b32 v2, v0
	s_add_i32 s6, 0, 0x23804
	v_mov_b32_e32 v0, s6
	ds_read_b32 v0, v0
	s_waitcnt lgkmcnt(1)
	v_cmp_ne_u32_e32 vcc, 0, v2
	s_cbranch_vccnz .LBB0_833
	s_add_u32 s6, s30, 0x3181200
	s_addc_u32 s7, s31, 0
	s_add_u32 s8, s30, 0x3181400
	s_addc_u32 s9, s31, 0
	s_add_u32 s10, s30, 0x3181500
	s_addc_u32 s11, s31, 0
	s_add_u32 s12, s30, 0x3181600
	s_addc_u32 s13, s31, 0
	s_add_u32 s14, s30, 0x3181700
	s_addc_u32 s15, s31, 0
	s_add_u32 s16, s30, 0x3181800
	s_addc_u32 s17, s31, 0
	s_add_u32 s18, s30, 0x3181900
	s_addc_u32 s19, s31, 0
	s_add_u32 s20, s30, 0x3181a00
	s_addc_u32 s21, s31, 0
	s_add_u32 s22, s30, 0x3181b00
	s_addc_u32 s23, s31, 0
	s_add_u32 s24, s30, 0x3181c00
	s_addc_u32 s25, s31, 0
	s_add_u32 s26, s30, 0x3181d00
	s_addc_u32 s27, s31, 0
	s_add_u32 s40, s30, 0x3181e00
	s_addc_u32 s41, s31, 0
	s_add_u32 s42, s30, 0x3181f00
	s_addc_u32 s43, s31, 0
	s_add_u32 s44, s30, 0x3182000
	s_addc_u32 s45, s31, 0
	s_add_u32 s46, s30, 0x3182100
	s_addc_u32 s47, s31, 0
	s_add_u32 s48, s30, 0x3182200
	s_addc_u32 s49, s31, 0
	s_mul_i32 s33, s39, s73
	s_add_u32 s50, s30, 0x3182300
	s_mul_i32 s33, s33, s38
	s_addc_u32 s51, s31, 0
	s_mov_b32 s34, 1
	v_mov_b32_e32 v16, 0
	s_branch .LBB0_821

; #define LAS __attribute__((address_space(3)))
;     __device__ __forceinline__ const float* in(int i) const { return (const float*)ptr(i); }
;     __device__ __forceinline__ unsigned char* ws() const { return (unsigned char*)ptr(37); }
; #define ws (p.ws())
; __device__ __forceinline__ void phase_lora(const Ctx& p, LAS unsigned char* lds) {
;     const int tid = threadIdx.x, lane = tid & 63, wave = __builtin_amdgcn_readfirstlane(tid >> 6), q = lane & 15, g = lane >> 4;
;     const bf16_t* ZRW = (const bf16_t*)(p.ws() + WS_ZRW);
;     float* DEC = (float*)(p.ws() + WS_DEC); bf16_t* AB = (bf16_t*)(p.ws() + WS_ABUF); bf16_t* GG = (bf16_t*)(p.ws() + WS_GG);
;     const bf16_t* w2T = (const bf16_t*)(p.ws() + WS_LW); const bf16_t* a2T = w2T + 512 * 64; const bf16_t* g2T = a2T + 512 * 64;
;     LAS bf16_t* X = (LAS bf16_t*)(lds + wave * 16 * 264 * 2);
;     const float* mu = p.in(17) + 1536;
.LBB0_870:
	s_cmp_lt_i32 s36, 6
	s_cselect_b64 s[4:5], -1, 0
	s_and_b64 s[10:11], s[4:5], s[2:3]
	s_andn2_b64 vcc, exec, s[10:11]
	s_cbranch_vccnz .LBB0_1564
	s_waitcnt vmcnt(0)
	v_mov_b32_e32 v0, 0x23528
	v_mov_b32_e32 v1, 0x23488
	v_mov_b32_e32 v2, 0x23428
	v_mov_b32_e32 v3, 0x23490
	v_mov_b32_e32 v4, 0x234a0
	ds_read_b64 v[6:7], v0
	ds_read_b64 v[8:9], v1
	ds_read_b64 v[10:11], v2
	ds_read_b64 v[12:13], v3
	ds_read_b64 v[14:15], v4
	v_readfirstlane_b32 s2, v180
	s_waitcnt lgkmcnt(0)
	v_readfirstlane_b32 s12, v6
	v_readfirstlane_b32 s13, v7
	v_readfirstlane_b32 s16, v8
	v_readfirstlane_b32 s17, v9
	v_readfirstlane_b32 s18, v10
	v_readfirstlane_b32 s19, v11
	v_readfirstlane_b32 s20, v12
	v_readfirstlane_b32 s21, v13
	v_readfirstlane_b32 s22, v14
	v_readfirstlane_b32 s23, v15
	s_nop 4
	s_lshr_b32 s27, s2, 6
	s_and_b32 s2, s27, 3
	s_lshr_b32 s56, s27, 2
	s_mul_i32 s2, s2, s38
	s_add_i32 s26, s2, s28
	s_add_u32 s14, s12, 0x8340000
	s_addc_u32 s15, s13, 0
	s_add_u32 s16, s16, 0x1800
	s_addc_u32 s17, s17, 0
	s_add_u32 s24, s12, 0x3190000
	s_addc_u32 s25, s13, 0
	s_add_u32 s40, s12, 0x31a0000
	s_addc_u32 s41, s13, 0
	s_add_u32 s42, s12, 0x31b0000
	s_addc_u32 s43, s13, 0
	s_add_u32 s44, s12, 0x3200000
	s_addc_u32 s45, s13, 0
	s_add_u32 s46, s12, 0x4240000
	s_addc_u32 s47, s13, 0
	s_add_u32 s54, s12, 0xfd20000
	s_addc_u32 s55, s13, 0
	v_and_b32_e32 v0, 63, v180
	v_lshrrev_b32_e32 v1, 2, v0
	v_and_b32_e32 v2, 3, v0
	v_and_b32_e32 v10, 15, v0
	v_lshrrev_b32_e32 v11, 4, v0
	v_cmp_eq_u32_e32 vcc, 0, v2
	v_mov_b32_e32 v12, 0xbfb8aa3b
	v_mov_b32_e32 v13, 0x4038aa3b
	v_cndmask_b32_e32 v7, v12, v13, vcc
	v_mov_b32_e32 v12, 1.0
	v_mov_b32_e32 v13, -2.0
	v_cndmask_b32_e32 v8, v12, v13, vcc
	v_mov_b32_e32 v12, 0
	v_mov_b32_e32 v13, 1.0
	v_cndmask_b32_e32 v9, v12, v13, vcc
	v_cmp_eq_u32_e64 s[48:49], 1, v2
	s_mul_i32 s3, s27, 0x2100
	v_mul_u32_u24_e32 v6, 0x210, v1
	v_lshl_add_u32 v6, v2, 7, v6
	v_add_u32_e32 v6, s3, v6
	v_mul_u32_u24_e32 v14, 0x210, v10
	v_lshl_add_u32 v14, v11, 4, v14
	v_add_u32_e32 v14, s3, v14
	v_lshlrev_b32_e32 v5, 8, v2
	s_lshr_b32 s2, s28, 3
	s_and_b32 s2, s2, 31
	s_lshl_b32 s2, s2, 13
	v_lshlrev_b32_e32 v12, 4, v180
	v_add_u32_e32 v12, s2, v12
	v_and_b32_e32 v13, 0x7f, v180
	v_lshlrev_b32_e32 v13, 4, v13
	global_load_dwordx4 v[164:167], v12, s[24:25]
	global_load_dwordx4 v[168:171], v13, s[20:21]
	global_load_dwordx4 v[172:175], v13, s[22:23]
	s_mov_b32 s57, 0

; #define LAS __attribute__((address_space(3)))
; __device__ __forceinline__ float sigmoidf_(float x) { return frcp(1.f + fexp2(-1.4426950408889634f * x)); }
; __device__ __forceinline__ void phase_lora(const Ctx& p, LAS unsigned char* lds) {
;     ...
;         asm volatile("s_waitcnt lgkmcnt(0)" ::: "memory");
;         bf16x8 bx[8];
; #pragma unroll
;         for (int ks = 0; ks < 8; ++ks) bx[ks] = *(const LAS bf16x8*)(X + q * 264 + ks * 32 + 8 * g);
;         const int row = r0 + q;
;         struct WF { bf16x8 w[2], a[2], gq[4]; f32x4 w0, a0; };
;         auto ldw = [&](WF& f, int nt) {
;             const int n = nt * 16 + q, c = nt * 16 + 4 * g;
; #pragma unroll
;             for (int ks = 0; ks < 2; ++ks) { f.w[ks] = *(const bf16x8*)(w2T + n * 64 + ks * 32 + 8 * g); f.a[ks] = *(const bf16x8*)(a2T + n * 64 + ks * 32 + 8 * g); }
; #pragma unroll
;             for (int ks = 0; ks < 4; ++ks) f.gq[ks] = *(const bf16x8*)(g2T + n * 128 + ks * 32 + 8 * g);
;             f.w0 = *(const f32x4*)(p.in(18) + c); f.a0 = *(const f32x4*)(p.in(20) + c);
;         };
;         auto tile = [&](const WF& f, int nt) {
;             f32x4 aw = (f32x4){0.f, 0.f, 0.f, 0.f}, aa = aw, ag = aw;
; #pragma unroll
;             for (int ks = 0; ks < 2; ++ks) { aw = __builtin_amdgcn_mfma_f32_16x16x32_bf16(f.w[ks], bx[ks], aw, 0, 0, 0); aa = __builtin_amdgcn_mfma_f32_16x16x32_bf16(f.a[ks], bx[2 + ks], aa, 0, 0, 0); }
; #pragma unroll
;             for (int ks = 0; ks < 4; ++ks) ag = __builtin_amdgcn_mfma_f32_16x16x32_bf16(f.gq[ks], bx[4 + ks], ag, 0, 0, 0);
;             const int c = nt * 16 + 4 * g;
;             f32x4 dec; float av[4];
; #pragma unroll
;             for (int e = 0; e < 4; ++e) {
;                 const float x = f.w0[e] + aw[e];
;                 const float sp = fmaxf(-x, 0.f) + log1pf(expf(-fabsf(x)));
;                 dec[e] = expf(-expf(-sp - 0.5f));
;                 av[e] = sigmoidf_(f.a0[e] + aa[e]);
;             }
;             *(f32x4*)(DEC + (size_t)row * 512 + c) = dec;
;             *(u32x2*)(AB + (size_t)row * 512 + c) = (u32x2){pk2(av[0], av[1]), pk2(av[2], av[3])};
;             *(u32x2*)(GG + (size_t)row * 512 + c) = (u32x2){pk2(ag[0], ag[1]), pk2(ag[2], ag[3])};
;         };
;         WF fa, fb;
;         ldw(fa, 0);
; #pragma unroll 1
;         for (int nt = 0; nt < 32; nt += 2) {
;             ldw(fb, nt + 1);
.Llora_nf7:
	v_sub_f32_e32 v152, v152, v144
	v_sub_f32_e32 v153, v153, v145
	v_sub_f32_e32 v154, v154, v146
	v_sub_f32_e32 v155, v155, v147
	v_sub_f32_e32 v156, v156, v148
	v_sub_f32_e32 v157, v157, v149
	v_sub_f32_e32 v158, v158, v150
	v_sub_f32_e32 v159, v159, v151
	v_fmac_f32_e32 v144, v152, v136
	v_fmac_f32_e32 v145, v153, v137
	v_fmac_f32_e32 v146, v154, v138
	v_fmac_f32_e32 v147, v155, v139
	v_fmac_f32_e32 v148, v156, v140
	v_fmac_f32_e32 v149, v157, v141
	v_fmac_f32_e32 v150, v158, v142
	v_fmac_f32_e32 v151, v159, v143
	v_mul_f32_e32 v152, v7, v144
	v_mul_f32_e32 v153, v7, v145
	v_mul_f32_e32 v154, v7, v146
	v_mul_f32_e32 v155, v7, v147
	v_mul_f32_e32 v156, v7, v148
	v_mul_f32_e32 v157, v7, v149
	v_mul_f32_e32 v158, v7, v150
	v_mul_f32_e32 v159, v7, v151
	v_exp_f32_e32 v152, v152
	v_exp_f32_e32 v153, v153
	v_exp_f32_e32 v154, v154
	v_exp_f32_e32 v155, v155
	v_exp_f32_e32 v156, v156
	v_exp_f32_e32 v157, v157
	v_exp_f32_e32 v158, v158
	v_exp_f32_e32 v159, v159
	v_add_f32_e32 v152, 1.0, v152
	v_add_f32_e32 v153, 1.0, v153
	v_add_f32_e32 v154, 1.0, v154
	v_add_f32_e32 v155, 1.0, v155
	v_add_f32_e32 v156, 1.0, v156
	v_add_f32_e32 v157, 1.0, v157
	v_add_f32_e32 v158, 1.0, v158
	v_add_f32_e32 v159, 1.0, v159
	v_rcp_f32_e32 v152, v152
	v_rcp_f32_e32 v153, v153
	v_rcp_f32_e32 v154, v154
	v_rcp_f32_e32 v155, v155
	v_rcp_f32_e32 v156, v156
	v_rcp_f32_e32 v157, v157
	v_rcp_f32_e32 v158, v158
	v_rcp_f32_e32 v159, v159
	v_fma_f32 v152, v152, v8, v9
	v_fma_f32 v153, v153, v8, v9
	v_fma_f32 v154, v154, v8, v9
	v_fma_f32 v155, v155, v8, v9
	v_fma_f32 v156, v156, v8, v9
	v_fma_f32 v157, v157, v8, v9
	v_fma_f32 v158, v158, v8, v9
	v_fma_f32 v159, v159, v8, v9
	v_cndmask_b32_e64 v152, v152, v144, s[48:49]
	v_cndmask_b32_e64 v153, v153, v145, s[48:49]
	v_cndmask_b32_e64 v154, v154, v146, s[48:49]
	v_cndmask_b32_e64 v155, v155, v147, s[48:49]
	v_cndmask_b32_e64 v156, v156, v148, s[48:49]
	v_cndmask_b32_e64 v157, v157, v149, s[48:49]
	v_cndmask_b32_e64 v158, v158, v150, s[48:49]
	v_cndmask_b32_e64 v159, v159, v151, s[48:49]
	v_cvt_pk_bf16_f32 v160, v152, v153
	v_cvt_pk_bf16_f32 v161, v154, v155
	v_cvt_pk_bf16_f32 v162, v156, v157
	v_cvt_pk_bf16_f32 v163, v158, v159
	ds_write_b128 v6, v[160:163] offset:112
	s_waitcnt lgkmcnt(0)
	ds_read_b128 v[184:187], v14 offset:0
	ds_read_b128 v[188:191], v14 offset:64
	ds_read_b128 v[192:195], v14 offset:128
	ds_read_b128 v[196:199], v14 offset:192
	ds_read_b128 v[200:203], v14 offset:256
	ds_read_b128 v[204:207], v14 offset:320
	ds_read_b128 v[208:211], v14 offset:384
	ds_read_b128 v[212:215], v14 offset:448
	s_lshl_b32 s2, s26, 4
	v_add_u32_e32 v137, s2, v10
	v_lshl_add_u32 v132, v11, 4, v10
	v_lshlrev_b32_e32 v132, 4, v132
	v_mov_b32_e32 v133, v132
	v_lshlrev_b32_e32 v134, 4, v11
	v_lshlrev_b32_e32 v135, 11, v137
	v_lshl_add_u32 v135, v11, 4, v135
	v_lshlrev_b32_e32 v136, 10, v137
	v_lshl_add_u32 v136, v11, 3, v136
	s_cmp_lg_u32 s57, 0
	s_cbranch_scc1 .Llora_single
	s_lshl_b32 s2, s56, 15
	v_add_u32_e32 v132, s2, v132
	s_lshl_b32 s2, s56, 16
	v_add_u32_e32 v133, s2, v133
	s_lshl_b32 s2, s56, 10
	v_add_u32_e32 v134, s2, v134
	v_add_u32_e32 v135, s2, v135
	s_lshl_b32 s2, s56, 9
	v_add_u32_e32 v136, s2, v136
	global_load_dwordx4 v[16:19], v132, s[24:25]
	global_load_dwordx4 v[20:23], v132, s[24:25] offset:1024
	global_load_dwordx4 v[24:27], v132, s[40:41]
	global_load_dwordx4 v[28:31], v132, s[40:41] offset:1024
	global_load_dwordx4 v[32:35], v133, s[42:43]
	global_load_dwordx4 v[36:39], v133, s[42:43] offset:1024
	global_load_dwordx4 v[40:43], v133, s[42:43] offset:2048
	global_load_dwordx4 v[44:47], v133, s[42:43] offset:3072
	global_load_dwordx4 v[48:51], v134, s[20:21]
	global_load_dwordx4 v[52:55], v134, s[22:23]
	v_add_u32_e32 v132, 0x800, v132
	v_add_u32_e32 v133, 0x1000, v133
	v_add_u32_e32 v134, 64, v134
	s_waitcnt lgkmcnt(0)
	global_load_dwordx4 v[56:59], v132, s[24:25]
	global_load_dwordx4 v[60:63], v132, s[24:25] offset:1024
	global_load_dwordx4 v[64:67], v132, s[40:41]
	global_load_dwordx4 v[68:71], v132, s[40:41] offset:1024
	global_load_dwordx4 v[72:75], v133, s[42:43]
	global_load_dwordx4 v[76:79], v133, s[42:43] offset:1024
	global_load_dwordx4 v[80:83], v133, s[42:43] offset:2048
	global_load_dwordx4 v[84:87], v133, s[42:43] offset:3072
	global_load_dwordx4 v[88:91], v134, s[20:21]
	global_load_dwordx4 v[92:95], v134, s[22:23]
	s_waitcnt vmcnt(10)
; __device__ __forceinline__ unsigned pk2(float lo, float hi) { f32x2 v = {lo, hi}; bf16x2_t b = __builtin_convertvector(v, bf16x2_t); return __builtin_bit_cast(unsigned, b); }
; __device__ __forceinline__ float sigmoidf_(float x) { return frcp(1.f + fexp2(-1.4426950408889634f * x)); }
; __device__ __forceinline__ void phase_lora(const Ctx& p, LAS unsigned char* lds) {
;     ...
;         auto tile = [&](const WF& f, int nt) {
;             f32x4 aw = (f32x4){0.f, 0.f, 0.f, 0.f}, aa = aw, ag = aw;
; #pragma unroll
;             for (int ks = 0; ks < 2; ++ks) { aw = __builtin_amdgcn_mfma_f32_16x16x32_bf16(f.w[ks], bx[ks], aw, 0, 0, 0); aa = __builtin_amdgcn_mfma_f32_16x16x32_bf16(f.a[ks], bx[2 + ks], aa, 0, 0, 0); }
; #pragma unroll
;             for (int ks = 0; ks < 4; ++ks) ag = __builtin_amdgcn_mfma_f32_16x16x32_bf16(f.gq[ks], bx[4 + ks], ag, 0, 0, 0);
;             const int c = nt * 16 + 4 * g;
;             f32x4 dec; float av[4];
; #pragma unroll
;             for (int e = 0; e < 4; ++e) {
;                 const float x = f.w0[e] + aw[e];
;                 const float sp = fmaxf(-x, 0.f) + log1pf(expf(-fabsf(x)));
;                 dec[e] = expf(-expf(-sp - 0.5f));
;                 av[e] = sigmoidf_(f.a0[e] + aa[e]);
;             }
;             *(f32x4*)(DEC + (size_t)row * 512 + c) = dec;
;             *(u32x2*)(AB + (size_t)row * 512 + c) = (u32x2){pk2(av[0], av[1]), pk2(av[2], av[3])};
;             *(u32x2*)(GG + (size_t)row * 512 + c) = (u32x2){pk2(ag[0], ag[1]), pk2(ag[2], ag[3])};
;         };
;         WF fa, fb;
;         ldw(fa, 0);
; #pragma unroll 1
;         for (int nt = 0; nt < 32; nt += 2) {
;             ldw(fb, nt + 1);
;             tile(fa, nt);
;             ldw(fa, (nt + 2) & 31);
;             tile(fb, nt + 1);
	v_mfma_f32_16x16x32_bf16 v[96:99], v[16:19], v[184:187], 0
	v_mfma_f32_16x16x32_bf16 v[100:103], v[24:27], v[192:195], 0
	v_mfma_f32_16x16x32_bf16 v[104:107], v[32:35], v[200:203], 0
	v_mfma_f32_16x16x32_bf16 v[96:99], v[20:23], v[188:191], v[96:99]
	v_mfma_f32_16x16x32_bf16 v[100:103], v[28:31], v[196:199], v[100:103]
	v_mfma_f32_16x16x32_bf16 v[104:107], v[36:39], v[204:207], v[104:107]
	v_mfma_f32_16x16x32_bf16 v[104:107], v[40:43], v[208:211], v[104:107]
	v_mfma_f32_16x16x32_bf16 v[104:107], v[44:47], v[212:215], v[104:107]
	v_add_u32_e32 v132, 0x800, v132
	v_add_u32_e32 v133, 0x1000, v133
	v_add_u32_e32 v134, 64, v134
	s_nop 4
	v_add_f32_e32 v108, v48, v96
	v_add_f32_e32 v109, v49, v97
	v_add_f32_e32 v110, v50, v98
	v_add_f32_e32 v111, v51, v99
	v_add_f32_e32 v112, v52, v100
	v_add_f32_e32 v113, v53, v101
	v_add_f32_e32 v114, v54, v102
	v_add_f32_e32 v115, v55, v103
	v_mul_f32_e32 v108, 0xbfb8aa3b, v108
	v_mul_f32_e32 v109, 0xbfb8aa3b, v109
	v_mul_f32_e32 v110, 0xbfb8aa3b, v110
	v_mul_f32_e32 v111, 0xbfb8aa3b, v111
	v_mul_f32_e32 v112, 0xbfb8aa3b, v112
	v_mul_f32_e32 v113, 0xbfb8aa3b, v113
	v_mul_f32_e32 v114, 0xbfb8aa3b, v114
	v_mul_f32_e32 v115, 0xbfb8aa3b, v115
	v_exp_f32_e32 v108, v108
	v_exp_f32_e32 v109, v109
	v_exp_f32_e32 v110, v110
	v_exp_f32_e32 v111, v111
	v_exp_f32_e32 v112, v112
	v_exp_f32_e32 v113, v113
	v_exp_f32_e32 v114, v114
	v_exp_f32_e32 v115, v115
	v_add_f32_e32 v108, 1.0, v108
	v_add_f32_e32 v109, 1.0, v109
	v_add_f32_e32 v110, 1.0, v110
	v_add_f32_e32 v111, 1.0, v111
	v_add_f32_e32 v112, 1.0, v112
	v_add_f32_e32 v113, 1.0, v113
	v_add_f32_e32 v114, 1.0, v114
	v_add_f32_e32 v115, 1.0, v115
	v_rcp_f32_e32 v108, v108
	v_rcp_f32_e32 v109, v109
	v_rcp_f32_e32 v110, v110
	v_rcp_f32_e32 v111, v111
	v_rcp_f32_e32 v112, v112
	v_rcp_f32_e32 v113, v113
	v_rcp_f32_e32 v114, v114
	v_rcp_f32_e32 v115, v115
	v_mul_f32_e32 v108, 0xbf60028b, v108
	v_mul_f32_e32 v109, 0xbf60028b, v109
	v_mul_f32_e32 v110, 0xbf60028b, v110
	v_mul_f32_e32 v111, 0xbf60028b, v111
	v_cvt_pk_bf16_f32 v116, v112, v113
	v_cvt_pk_bf16_f32 v117, v114, v115
	v_exp_f32_e32 v108, v108
	v_exp_f32_e32 v109, v109
	v_exp_f32_e32 v110, v110
	v_exp_f32_e32 v111, v111
	v_cvt_pk_bf16_f32 v118, v104, v105
	v_cvt_pk_bf16_f32 v119, v106, v107
	global_store_dwordx2 v136, v[116:117], s[44:45]
	global_store_dwordx2 v136, v[118:119], s[46:47]
	global_store_dwordx4 v135, v[108:111], s[54:55]
	v_add_u32_e32 v136, 32, v136
	v_add_u32_e32 v135, 64, v135
	global_load_dwordx4 v[16:19], v132, s[24:25]
	global_load_dwordx4 v[20:23], v132, s[24:25] offset:1024
	global_load_dwordx4 v[24:27], v132, s[40:41]
	global_load_dwordx4 v[28:31], v132, s[40:41] offset:1024
	global_load_dwordx4 v[32:35], v133, s[42:43]
	global_load_dwordx4 v[36:39], v133, s[42:43] offset:1024
	global_load_dwordx4 v[40:43], v133, s[42:43] offset:2048
	global_load_dwordx4 v[44:47], v133, s[42:43] offset:3072
	global_load_dwordx4 v[48:51], v134, s[20:21]
	global_load_dwordx4 v[52:55], v134, s[22:23]
	s_waitcnt vmcnt(13)
	v_mfma_f32_16x16x32_bf16 v[96:99], v[56:59], v[184:187], 0
	v_mfma_f32_16x16x32_bf16 v[100:103], v[64:67], v[192:195], 0
	v_mfma_f32_16x16x32_bf16 v[104:107], v[72:75], v[200:203], 0
	v_mfma_f32_16x16x32_bf16 v[96:99], v[60:63], v[188:191], v[96:99]
	v_mfma_f32_16x16x32_bf16 v[100:103], v[68:71], v[196:199], v[100:103]
	v_mfma_f32_16x16x32_bf16 v[104:107], v[76:79], v[204:207], v[104:107]
	v_mfma_f32_16x16x32_bf16 v[104:107], v[80:83], v[208:211], v[104:107]
	v_mfma_f32_16x16x32_bf16 v[104:107], v[84:87], v[212:215], v[104:107]
	v_add_u32_e32 v132, 0x800, v132
	v_add_u32_e32 v133, 0x1000, v133
	v_add_u32_e32 v134, 64, v134
	s_nop 4
	v_add_f32_e32 v108, v88, v96
	v_add_f32_e32 v109, v89, v97
	v_add_f32_e32 v110, v90, v98
	v_add_f32_e32 v111, v91, v99
	v_add_f32_e32 v112, v92, v100
	v_add_f32_e32 v113, v93, v101
	v_add_f32_e32 v114, v94, v102
	v_add_f32_e32 v115, v95, v103
	v_mul_f32_e32 v108, 0xbfb8aa3b, v108
	v_mul_f32_e32 v109, 0xbfb8aa3b, v109
	v_mul_f32_e32 v110, 0xbfb8aa3b, v110
	v_mul_f32_e32 v111, 0xbfb8aa3b, v111
	v_mul_f32_e32 v112, 0xbfb8aa3b, v112
	v_mul_f32_e32 v113, 0xbfb8aa3b, v113
	v_mul_f32_e32 v114, 0xbfb8aa3b, v114
	v_mul_f32_e32 v115, 0xbfb8aa3b, v115
	v_exp_f32_e32 v108, v108
	v_exp_f32_e32 v109, v109
	v_exp_f32_e32 v110, v110
	v_exp_f32_e32 v111, v111
	v_exp_f32_e32 v112, v112
	v_exp_f32_e32 v113, v113
	v_exp_f32_e32 v114, v114
	v_exp_f32_e32 v115, v115
	v_add_f32_e32 v108, 1.0, v108
	v_add_f32_e32 v109, 1.0, v109
	v_add_f32_e32 v110, 1.0, v110
	v_add_f32_e32 v111, 1.0, v111
	v_add_f32_e32 v112, 1.0, v112
	v_add_f32_e32 v113, 1.0, v113
	v_add_f32_e32 v114, 1.0, v114
	v_add_f32_e32 v115, 1.0, v115
	v_rcp_f32_e32 v108, v108
	v_rcp_f32_e32 v109, v109
	v_rcp_f32_e32 v110, v110
	v_rcp_f32_e32 v111, v111
	v_rcp_f32_e32 v112, v112
	v_rcp_f32_e32 v113, v113
	v_rcp_f32_e32 v114, v114
	v_rcp_f32_e32 v115, v115
	v_mul_f32_e32 v108, 0xbf60028b, v108
	v_mul_f32_e32 v109, 0xbf60028b, v109
	v_mul_f32_e32 v110, 0xbf60028b, v110
	v_mul_f32_e32 v111, 0xbf60028b, v111
	v_cvt_pk_bf16_f32 v116, v112, v113
	v_cvt_pk_bf16_f32 v117, v114, v115
	v_exp_f32_e32 v108, v108
	v_exp_f32_e32 v109, v109
	v_exp_f32_e32 v110, v110
	v_exp_f32_e32 v111, v111
	v_cvt_pk_bf16_f32 v118, v104, v105
	v_cvt_pk_bf16_f32 v119, v106, v107
	global_store_dwordx2 v136, v[116:117], s[44:45]
	global_store_dwordx2 v136, v[118:119], s[46:47]
	global_store_dwordx4 v135, v[108:111], s[54:55]
	v_add_u32_e32 v136, 32, v136
	v_add_u32_e32 v135, 64, v135
	s_movk_i32 s2, 6
; __device__ __forceinline__ unsigned pk2(float lo, float hi) { f32x2 v = {lo, hi}; bf16x2_t b = __builtin_convertvector(v, bf16x2_t); return __builtin_bit_cast(unsigned, b); }
; __device__ __forceinline__ float sigmoidf_(float x) { return frcp(1.f + fexp2(-1.4426950408889634f * x)); }
; __device__ __forceinline__ void phase_lora(const Ctx& p, LAS unsigned char* lds) {
;     ...
;         auto tile = [&](const WF& f, int nt) {
;             f32x4 aw = (f32x4){0.f, 0.f, 0.f, 0.f}, aa = aw, ag = aw;
; #pragma unroll
;             for (int ks = 0; ks < 2; ++ks) { aw = __builtin_amdgcn_mfma_f32_16x16x32_bf16(f.w[ks], bx[ks], aw, 0, 0, 0); aa = __builtin_amdgcn_mfma_f32_16x16x32_bf16(f.a[ks], bx[2 + ks], aa, 0, 0, 0); }
; #pragma unroll
;             for (int ks = 0; ks < 4; ++ks) ag = __builtin_amdgcn_mfma_f32_16x16x32_bf16(f.gq[ks], bx[4 + ks], ag, 0, 0, 0);
;             const int c = nt * 16 + 4 * g;
;             f32x4 dec; float av[4];
; #pragma unroll
;             for (int e = 0; e < 4; ++e) {
;                 const float x = f.w0[e] + aw[e];
;                 const float sp = fmaxf(-x, 0.f) + log1pf(expf(-fabsf(x)));
;                 dec[e] = expf(-expf(-sp - 0.5f));
;                 av[e] = sigmoidf_(f.a0[e] + aa[e]);
;             }
;             *(f32x4*)(DEC + (size_t)row * 512 + c) = dec;
;             *(u32x2*)(AB + (size_t)row * 512 + c) = (u32x2){pk2(av[0], av[1]), pk2(av[2], av[3])};
;             *(u32x2*)(GG + (size_t)row * 512 + c) = (u32x2){pk2(ag[0], ag[1]), pk2(ag[2], ag[3])};
;         };
;         WF fa, fb;
;         ldw(fa, 0);
; #pragma unroll 1
;         for (int nt = 0; nt < 32; nt += 2) {
;             ldw(fb, nt + 1);
;             tile(fa, nt);
;             ldw(fa, (nt + 2) & 31);
;             tile(fb, nt + 1);
.Llora_nt:
	global_load_dwordx4 v[56:59], v132, s[24:25]
	global_load_dwordx4 v[60:63], v132, s[24:25] offset:1024
	global_load_dwordx4 v[64:67], v132, s[40:41]
	global_load_dwordx4 v[68:71], v132, s[40:41] offset:1024
	global_load_dwordx4 v[72:75], v133, s[42:43]
	global_load_dwordx4 v[76:79], v133, s[42:43] offset:1024
	global_load_dwordx4 v[80:83], v133, s[42:43] offset:2048
	global_load_dwordx4 v[84:87], v133, s[42:43] offset:3072
	global_load_dwordx4 v[88:91], v134, s[20:21]
	global_load_dwordx4 v[92:95], v134, s[22:23]
	s_waitcnt vmcnt(13)
	v_mfma_f32_16x16x32_bf16 v[96:99], v[16:19], v[184:187], 0
	v_mfma_f32_16x16x32_bf16 v[100:103], v[24:27], v[192:195], 0
	v_mfma_f32_16x16x32_bf16 v[104:107], v[32:35], v[200:203], 0
	v_mfma_f32_16x16x32_bf16 v[96:99], v[20:23], v[188:191], v[96:99]
	v_mfma_f32_16x16x32_bf16 v[100:103], v[28:31], v[196:199], v[100:103]
	v_mfma_f32_16x16x32_bf16 v[104:107], v[36:39], v[204:207], v[104:107]
	v_mfma_f32_16x16x32_bf16 v[104:107], v[40:43], v[208:211], v[104:107]
	v_mfma_f32_16x16x32_bf16 v[104:107], v[44:47], v[212:215], v[104:107]
	v_add_u32_e32 v132, 0x800, v132
	v_add_u32_e32 v133, 0x1000, v133
	v_add_u32_e32 v134, 64, v134
	s_nop 4
	v_add_f32_e32 v108, v48, v96
	v_add_f32_e32 v109, v49, v97
	v_add_f32_e32 v110, v50, v98
	v_add_f32_e32 v111, v51, v99
	v_add_f32_e32 v112, v52, v100
	v_add_f32_e32 v113, v53, v101
	v_add_f32_e32 v114, v54, v102
	v_add_f32_e32 v115, v55, v103
	v_mul_f32_e32 v108, 0xbfb8aa3b, v108
	v_mul_f32_e32 v109, 0xbfb8aa3b, v109
	v_mul_f32_e32 v110, 0xbfb8aa3b, v110
	v_mul_f32_e32 v111, 0xbfb8aa3b, v111
	v_mul_f32_e32 v112, 0xbfb8aa3b, v112
	v_mul_f32_e32 v113, 0xbfb8aa3b, v113
	v_mul_f32_e32 v114, 0xbfb8aa3b, v114
	v_mul_f32_e32 v115, 0xbfb8aa3b, v115
	v_exp_f32_e32 v108, v108
	v_exp_f32_e32 v109, v109
	v_exp_f32_e32 v110, v110
	v_exp_f32_e32 v111, v111
	v_exp_f32_e32 v112, v112
	v_exp_f32_e32 v113, v113
	v_exp_f32_e32 v114, v114
	v_exp_f32_e32 v115, v115
	v_add_f32_e32 v108, 1.0, v108
	v_add_f32_e32 v109, 1.0, v109
	v_add_f32_e32 v110, 1.0, v110
	v_add_f32_e32 v111, 1.0, v111
	v_add_f32_e32 v112, 1.0, v112
	v_add_f32_e32 v113, 1.0, v113
	v_add_f32_e32 v114, 1.0, v114
	v_add_f32_e32 v115, 1.0, v115
	v_rcp_f32_e32 v108, v108
	v_rcp_f32_e32 v109, v109
	v_rcp_f32_e32 v110, v110
	v_rcp_f32_e32 v111, v111
	v_rcp_f32_e32 v112, v112
	v_rcp_f32_e32 v113, v113
	v_rcp_f32_e32 v114, v114
	v_rcp_f32_e32 v115, v115
	v_mul_f32_e32 v108, 0xbf60028b, v108
	v_mul_f32_e32 v109, 0xbf60028b, v109
	v_mul_f32_e32 v110, 0xbf60028b, v110
	v_mul_f32_e32 v111, 0xbf60028b, v111
	v_cvt_pk_bf16_f32 v116, v112, v113
	v_cvt_pk_bf16_f32 v117, v114, v115
	v_exp_f32_e32 v108, v108
	v_exp_f32_e32 v109, v109
	v_exp_f32_e32 v110, v110
	v_exp_f32_e32 v111, v111
	v_cvt_pk_bf16_f32 v118, v104, v105
	v_cvt_pk_bf16_f32 v119, v106, v107
	global_store_dwordx2 v136, v[116:117], s[44:45]
	global_store_dwordx2 v136, v[118:119], s[46:47]
	global_store_dwordx4 v135, v[108:111], s[54:55]
	v_add_u32_e32 v136, 32, v136
	v_add_u32_e32 v135, 64, v135
	global_load_dwordx4 v[16:19], v132, s[24:25]
	global_load_dwordx4 v[20:23], v132, s[24:25] offset:1024
	global_load_dwordx4 v[24:27], v132, s[40:41]
	global_load_dwordx4 v[28:31], v132, s[40:41] offset:1024
	global_load_dwordx4 v[32:35], v133, s[42:43]
	global_load_dwordx4 v[36:39], v133, s[42:43] offset:1024
	global_load_dwordx4 v[40:43], v133, s[42:43] offset:2048
	global_load_dwordx4 v[44:47], v133, s[42:43] offset:3072
	global_load_dwordx4 v[48:51], v134, s[20:21]
	global_load_dwordx4 v[52:55], v134, s[22:23]
	s_waitcnt vmcnt(13)
	v_mfma_f32_16x16x32_bf16 v[96:99], v[56:59], v[184:187], 0
	v_mfma_f32_16x16x32_bf16 v[100:103], v[64:67], v[192:195], 0
	v_mfma_f32_16x16x32_bf16 v[104:107], v[72:75], v[200:203], 0
	v_mfma_f32_16x16x32_bf16 v[96:99], v[60:63], v[188:191], v[96:99]
	v_mfma_f32_16x16x32_bf16 v[100:103], v[68:71], v[196:199], v[100:103]
	v_mfma_f32_16x16x32_bf16 v[104:107], v[76:79], v[204:207], v[104:107]
	v_mfma_f32_16x16x32_bf16 v[104:107], v[80:83], v[208:211], v[104:107]
	v_mfma_f32_16x16x32_bf16 v[104:107], v[84:87], v[212:215], v[104:107]
	v_add_u32_e32 v132, 0x800, v132
	v_add_u32_e32 v133, 0x1000, v133
	v_add_u32_e32 v134, 64, v134
	s_nop 4
	v_add_f32_e32 v108, v88, v96
	v_add_f32_e32 v109, v89, v97
	v_add_f32_e32 v110, v90, v98
	v_add_f32_e32 v111, v91, v99
	v_add_f32_e32 v112, v92, v100
	v_add_f32_e32 v113, v93, v101
	v_add_f32_e32 v114, v94, v102
	v_add_f32_e32 v115, v95, v103
	v_mul_f32_e32 v108, 0xbfb8aa3b, v108
	v_mul_f32_e32 v109, 0xbfb8aa3b, v109
	v_mul_f32_e32 v110, 0xbfb8aa3b, v110
	v_mul_f32_e32 v111, 0xbfb8aa3b, v111
	v_mul_f32_e32 v112, 0xbfb8aa3b, v112
	v_mul_f32_e32 v113, 0xbfb8aa3b, v113
	v_mul_f32_e32 v114, 0xbfb8aa3b, v114
	v_mul_f32_e32 v115, 0xbfb8aa3b, v115
	v_exp_f32_e32 v108, v108
	v_exp_f32_e32 v109, v109
	v_exp_f32_e32 v110, v110
	v_exp_f32_e32 v111, v111
	v_exp_f32_e32 v112, v112
	v_exp_f32_e32 v113, v113
	v_exp_f32_e32 v114, v114
	v_exp_f32_e32 v115, v115
	v_add_f32_e32 v108, 1.0, v108
	v_add_f32_e32 v109, 1.0, v109
	v_add_f32_e32 v110, 1.0, v110
	v_add_f32_e32 v111, 1.0, v111
	v_add_f32_e32 v112, 1.0, v112
	v_add_f32_e32 v113, 1.0, v113
	v_add_f32_e32 v114, 1.0, v114
	v_add_f32_e32 v115, 1.0, v115
	v_rcp_f32_e32 v108, v108
	v_rcp_f32_e32 v109, v109
	v_rcp_f32_e32 v110, v110
	v_rcp_f32_e32 v111, v111
	v_rcp_f32_e32 v112, v112
	v_rcp_f32_e32 v113, v113
	v_rcp_f32_e32 v114, v114
	v_rcp_f32_e32 v115, v115
	v_mul_f32_e32 v108, 0xbf60028b, v108
	v_mul_f32_e32 v109, 0xbf60028b, v109
	v_mul_f32_e32 v110, 0xbf60028b, v110
	v_mul_f32_e32 v111, 0xbf60028b, v111
	v_cvt_pk_bf16_f32 v116, v112, v113
	v_cvt_pk_bf16_f32 v117, v114, v115
	v_exp_f32_e32 v108, v108
	v_exp_f32_e32 v109, v109
	v_exp_f32_e32 v110, v110
	v_exp_f32_e32 v111, v111
	v_cvt_pk_bf16_f32 v118, v104, v105
	v_cvt_pk_bf16_f32 v119, v106, v107
	global_store_dwordx2 v136, v[116:117], s[44:45]
	global_store_dwordx2 v136, v[118:119], s[46:47]
	global_store_dwordx4 v135, v[108:111], s[54:55]
	v_add_u32_e32 v136, 32, v136
	v_add_u32_e32 v135, 64, v135
	s_sub_u32 s2, s2, 1
	s_cmp_lg_u32 s2, 0
	s_cbranch_scc1 .Llora_nt
; __device__ __forceinline__ unsigned pk2(float lo, float hi) { f32x2 v = {lo, hi}; bf16x2_t b = __builtin_convertvector(v, bf16x2_t); return __builtin_bit_cast(unsigned, b); }
; __device__ __forceinline__ float sigmoidf_(float x) { return frcp(1.f + fexp2(-1.4426950408889634f * x)); }
; __device__ __forceinline__ void phase_lora(const Ctx& p, LAS unsigned char* lds) {
;     ...
;         auto tile = [&](const WF& f, int nt) {
;             f32x4 aw = (f32x4){0.f, 0.f, 0.f, 0.f}, aa = aw, ag = aw;
; #pragma unroll
;             for (int ks = 0; ks < 2; ++ks) { aw = __builtin_amdgcn_mfma_f32_16x16x32_bf16(f.w[ks], bx[ks], aw, 0, 0, 0); aa = __builtin_amdgcn_mfma_f32_16x16x32_bf16(f.a[ks], bx[2 + ks], aa, 0, 0, 0); }
; #pragma unroll
;             for (int ks = 0; ks < 4; ++ks) ag = __builtin_amdgcn_mfma_f32_16x16x32_bf16(f.gq[ks], bx[4 + ks], ag, 0, 0, 0);
;             const int c = nt * 16 + 4 * g;
;             f32x4 dec; float av[4];
; #pragma unroll
;             for (int e = 0; e < 4; ++e) {
;                 const float x = f.w0[e] + aw[e];
;                 const float sp = fmaxf(-x, 0.f) + log1pf(expf(-fabsf(x)));
;                 dec[e] = expf(-expf(-sp - 0.5f));
;                 av[e] = sigmoidf_(f.a0[e] + aa[e]);
;             }
;             *(f32x4*)(DEC + (size_t)row * 512 + c) = dec;
;             *(u32x2*)(AB + (size_t)row * 512 + c) = (u32x2){pk2(av[0], av[1]), pk2(av[2], av[3])};
;             *(u32x2*)(GG + (size_t)row * 512 + c) = (u32x2){pk2(ag[0], ag[1]), pk2(ag[2], ag[3])};
;         };
;         WF fa, fb;
;         ldw(fa, 0);
; #pragma unroll 1
;         for (int nt = 0; nt < 32; nt += 2) {
;             ldw(fb, nt + 1);
;             tile(fa, nt);
;             ldw(fa, (nt + 2) & 31);
;             tile(fb, nt + 1);
	global_load_dwordx4 v[56:59], v132, s[24:25]
	global_load_dwordx4 v[60:63], v132, s[24:25] offset:1024
	global_load_dwordx4 v[64:67], v132, s[40:41]
	global_load_dwordx4 v[68:71], v132, s[40:41] offset:1024
	global_load_dwordx4 v[72:75], v133, s[42:43]
	global_load_dwordx4 v[76:79], v133, s[42:43] offset:1024
	global_load_dwordx4 v[80:83], v133, s[42:43] offset:2048
	global_load_dwordx4 v[84:87], v133, s[42:43] offset:3072
	global_load_dwordx4 v[88:91], v134, s[20:21]
	global_load_dwordx4 v[92:95], v134, s[22:23]
	s_waitcnt vmcnt(13)
	v_mfma_f32_16x16x32_bf16 v[96:99], v[16:19], v[184:187], 0
	v_mfma_f32_16x16x32_bf16 v[100:103], v[24:27], v[192:195], 0
	v_mfma_f32_16x16x32_bf16 v[104:107], v[32:35], v[200:203], 0
	v_mfma_f32_16x16x32_bf16 v[96:99], v[20:23], v[188:191], v[96:99]
	v_mfma_f32_16x16x32_bf16 v[100:103], v[28:31], v[196:199], v[100:103]
	v_mfma_f32_16x16x32_bf16 v[104:107], v[36:39], v[204:207], v[104:107]
	v_mfma_f32_16x16x32_bf16 v[104:107], v[40:43], v[208:211], v[104:107]
	v_mfma_f32_16x16x32_bf16 v[104:107], v[44:47], v[212:215], v[104:107]
	v_add_u32_e32 v132, 0x800, v132
	v_add_u32_e32 v133, 0x1000, v133
	v_add_u32_e32 v134, 64, v134
	s_nop 4
	v_add_f32_e32 v108, v48, v96
	v_add_f32_e32 v109, v49, v97
	v_add_f32_e32 v110, v50, v98
	v_add_f32_e32 v111, v51, v99
	v_add_f32_e32 v112, v52, v100
	v_add_f32_e32 v113, v53, v101
	v_add_f32_e32 v114, v54, v102
	v_add_f32_e32 v115, v55, v103
	v_mul_f32_e32 v108, 0xbfb8aa3b, v108
	v_mul_f32_e32 v109, 0xbfb8aa3b, v109
	v_mul_f32_e32 v110, 0xbfb8aa3b, v110
	v_mul_f32_e32 v111, 0xbfb8aa3b, v111
	v_mul_f32_e32 v112, 0xbfb8aa3b, v112
	v_mul_f32_e32 v113, 0xbfb8aa3b, v113
	v_mul_f32_e32 v114, 0xbfb8aa3b, v114
	v_mul_f32_e32 v115, 0xbfb8aa3b, v115
	v_exp_f32_e32 v108, v108
	v_exp_f32_e32 v109, v109
	v_exp_f32_e32 v110, v110
	v_exp_f32_e32 v111, v111
	v_exp_f32_e32 v112, v112
	v_exp_f32_e32 v113, v113
	v_exp_f32_e32 v114, v114
	v_exp_f32_e32 v115, v115
	v_add_f32_e32 v108, 1.0, v108
	v_add_f32_e32 v109, 1.0, v109
	v_add_f32_e32 v110, 1.0, v110
	v_add_f32_e32 v111, 1.0, v111
	v_add_f32_e32 v112, 1.0, v112
	v_add_f32_e32 v113, 1.0, v113
	v_add_f32_e32 v114, 1.0, v114
	v_add_f32_e32 v115, 1.0, v115
	v_rcp_f32_e32 v108, v108
	v_rcp_f32_e32 v109, v109
	v_rcp_f32_e32 v110, v110
	v_rcp_f32_e32 v111, v111
	v_rcp_f32_e32 v112, v112
	v_rcp_f32_e32 v113, v113
	v_rcp_f32_e32 v114, v114
	v_rcp_f32_e32 v115, v115
	v_mul_f32_e32 v108, 0xbf60028b, v108
	v_mul_f32_e32 v109, 0xbf60028b, v109
	v_mul_f32_e32 v110, 0xbf60028b, v110
	v_mul_f32_e32 v111, 0xbf60028b, v111
	v_cvt_pk_bf16_f32 v116, v112, v113
	v_cvt_pk_bf16_f32 v117, v114, v115
	v_exp_f32_e32 v108, v108
	v_exp_f32_e32 v109, v109
	v_exp_f32_e32 v110, v110
	v_exp_f32_e32 v111, v111
	v_cvt_pk_bf16_f32 v118, v104, v105
	v_cvt_pk_bf16_f32 v119, v106, v107
	global_store_dwordx2 v136, v[116:117], s[44:45]
	global_store_dwordx2 v136, v[118:119], s[46:47]
	global_store_dwordx4 v135, v[108:111], s[54:55]
	v_add_u32_e32 v136, 32, v136
	v_add_u32_e32 v135, 64, v135
	s_waitcnt vmcnt(3)
	v_mfma_f32_16x16x32_bf16 v[96:99], v[56:59], v[184:187], 0
	v_mfma_f32_16x16x32_bf16 v[100:103], v[64:67], v[192:195], 0
	v_mfma_f32_16x16x32_bf16 v[104:107], v[72:75], v[200:203], 0
	v_mfma_f32_16x16x32_bf16 v[96:99], v[60:63], v[188:191], v[96:99]
	v_mfma_f32_16x16x32_bf16 v[100:103], v[68:71], v[196:199], v[100:103]
	v_mfma_f32_16x16x32_bf16 v[104:107], v[76:79], v[204:207], v[104:107]
	v_mfma_f32_16x16x32_bf16 v[104:107], v[80:83], v[208:211], v[104:107]
	v_mfma_f32_16x16x32_bf16 v[104:107], v[84:87], v[212:215], v[104:107]
	v_add_u32_e32 v132, 0x800, v132
	v_add_u32_e32 v133, 0x1000, v133
	v_add_u32_e32 v134, 64, v134
	s_nop 4
	v_add_f32_e32 v108, v88, v96
	v_add_f32_e32 v109, v89, v97
	v_add_f32_e32 v110, v90, v98
	v_add_f32_e32 v111, v91, v99
	v_add_f32_e32 v112, v92, v100
	v_add_f32_e32 v113, v93, v101
	v_add_f32_e32 v114, v94, v102
	v_add_f32_e32 v115, v95, v103
	v_mul_f32_e32 v108, 0xbfb8aa3b, v108
	v_mul_f32_e32 v109, 0xbfb8aa3b, v109
	v_mul_f32_e32 v110, 0xbfb8aa3b, v110
	v_mul_f32_e32 v111, 0xbfb8aa3b, v111
	v_mul_f32_e32 v112, 0xbfb8aa3b, v112
	v_mul_f32_e32 v113, 0xbfb8aa3b, v113
	v_mul_f32_e32 v114, 0xbfb8aa3b, v114
	v_mul_f32_e32 v115, 0xbfb8aa3b, v115
	v_exp_f32_e32 v108, v108
	v_exp_f32_e32 v109, v109
	v_exp_f32_e32 v110, v110
	v_exp_f32_e32 v111, v111
	v_exp_f32_e32 v112, v112
	v_exp_f32_e32 v113, v113
	v_exp_f32_e32 v114, v114
	v_exp_f32_e32 v115, v115
	v_add_f32_e32 v108, 1.0, v108
	v_add_f32_e32 v109, 1.0, v109
	v_add_f32_e32 v110, 1.0, v110
	v_add_f32_e32 v111, 1.0, v111
	v_add_f32_e32 v112, 1.0, v112
	v_add_f32_e32 v113, 1.0, v113
	v_add_f32_e32 v114, 1.0, v114
	v_add_f32_e32 v115, 1.0, v115
	v_rcp_f32_e32 v108, v108
	v_rcp_f32_e32 v109, v109
	v_rcp_f32_e32 v110, v110
	v_rcp_f32_e32 v111, v111
	v_rcp_f32_e32 v112, v112
	v_rcp_f32_e32 v113, v113
	v_rcp_f32_e32 v114, v114
	v_rcp_f32_e32 v115, v115
	v_mul_f32_e32 v108, 0xbf60028b, v108
	v_mul_f32_e32 v109, 0xbf60028b, v109
	v_mul_f32_e32 v110, 0xbf60028b, v110
	v_mul_f32_e32 v111, 0xbf60028b, v111
	v_cvt_pk_bf16_f32 v116, v112, v113
	v_cvt_pk_bf16_f32 v117, v114, v115
	v_exp_f32_e32 v108, v108
	v_exp_f32_e32 v109, v109
	v_exp_f32_e32 v110, v110
	v_exp_f32_e32 v111, v111
	v_cvt_pk_bf16_f32 v118, v104, v105
	v_cvt_pk_bf16_f32 v119, v106, v107
	global_store_dwordx2 v136, v[116:117], s[44:45]
	global_store_dwordx2 v136, v[118:119], s[46:47]
	global_store_dwordx4 v135, v[108:111], s[54:55]
	v_add_u32_e32 v136, 32, v136
	v_add_u32_e32 v135, 64, v135
	s_cmp_lt_u32 s28, 32
	s_cbranch_scc0 .Llora_done
	s_mov_b32 s57, 1
	s_lshr_b32 s2, s28, 2
	s_add_i32 s26, s2, 0x400
	s_branch .Llora_item
; __device__ __forceinline__ unsigned pk2(float lo, float hi) { f32x2 v = {lo, hi}; bf16x2_t b = __builtin_convertvector(v, bf16x2_t); return __builtin_bit_cast(unsigned, b); }
; __device__ __forceinline__ float sigmoidf_(float x) { return frcp(1.f + fexp2(-1.4426950408889634f * x)); }
;     __device__ __forceinline__ const float* in(int i) const { return (const float*)ptr(i); }
; __device__ __forceinline__ void phase_lora(const Ctx& p, LAS unsigned char* lds) {
;     ...
;         auto ldw = [&](WF& f, int nt) {
;             const int n = nt * 16 + q, c = nt * 16 + 4 * g;
; #pragma unroll
;             for (int ks = 0; ks < 2; ++ks) { f.w[ks] = *(const bf16x8*)(w2T + n * 64 + ks * 32 + 8 * g); f.a[ks] = *(const bf16x8*)(a2T + n * 64 + ks * 32 + 8 * g); }
; #pragma unroll
;             for (int ks = 0; ks < 4; ++ks) f.gq[ks] = *(const bf16x8*)(g2T + n * 128 + ks * 32 + 8 * g);
;             f.w0 = *(const f32x4*)(p.in(18) + c); f.a0 = *(const f32x4*)(p.in(20) + c);
;         };
;         auto tile = [&](const WF& f, int nt) {
;             f32x4 aw = (f32x4){0.f, 0.f, 0.f, 0.f}, aa = aw, ag = aw;
; #pragma unroll
;             for (int ks = 0; ks < 2; ++ks) { aw = __builtin_amdgcn_mfma_f32_16x16x32_bf16(f.w[ks], bx[ks], aw, 0, 0, 0); aa = __builtin_amdgcn_mfma_f32_16x16x32_bf16(f.a[ks], bx[2 + ks], aa, 0, 0, 0); }
; #pragma unroll
;             for (int ks = 0; ks < 4; ++ks) ag = __builtin_amdgcn_mfma_f32_16x16x32_bf16(f.gq[ks], bx[4 + ks], ag, 0, 0, 0);
;             const int c = nt * 16 + 4 * g;
;             f32x4 dec; float av[4];
; #pragma unroll
;             for (int e = 0; e < 4; ++e) {
;                 const float x = f.w0[e] + aw[e];
;                 const float sp = fmaxf(-x, 0.f) + log1pf(expf(-fabsf(x)));
;                 dec[e] = expf(-expf(-sp - 0.5f));
;                 av[e] = sigmoidf_(f.a0[e] + aa[e]);
;             }
;             *(f32x4*)(DEC + (size_t)row * 512 + c) = dec;
;             *(u32x2*)(AB + (size_t)row * 512 + c) = (u32x2){pk2(av[0], av[1]), pk2(av[2], av[3])};
;             *(u32x2*)(GG + (size_t)row * 512 + c) = (u32x2){pk2(ag[0], ag[1]), pk2(ag[2], ag[3])};
;         };
.Llora_single:
	s_and_b32 s2, s28, 3
	s_lshl_b32 s2, s2, 3
	s_add_i32 s2, s2, s27
	s_lshl_b32 s3, s2, 11
	v_add_u32_e32 v132, s3, v132
	s_lshl_b32 s3, s2, 12
	v_add_u32_e32 v133, s3, v133
	s_lshl_b32 s3, s2, 6
	v_add_u32_e32 v134, s3, v134
	v_add_u32_e32 v135, s3, v135
	s_lshl_b32 s3, s2, 5
	v_add_u32_e32 v136, s3, v136
	global_load_dwordx4 v[16:19], v132, s[24:25]
	global_load_dwordx4 v[20:23], v132, s[24:25] offset:1024
	global_load_dwordx4 v[24:27], v132, s[40:41]
	global_load_dwordx4 v[28:31], v132, s[40:41] offset:1024
	global_load_dwordx4 v[32:35], v133, s[42:43]
	global_load_dwordx4 v[36:39], v133, s[42:43] offset:1024
	global_load_dwordx4 v[40:43], v133, s[42:43] offset:2048
	global_load_dwordx4 v[44:47], v133, s[42:43] offset:3072
	global_load_dwordx4 v[48:51], v134, s[20:21]
	global_load_dwordx4 v[52:55], v134, s[22:23]
	s_waitcnt lgkmcnt(0)
	s_waitcnt vmcnt(0)
	v_mfma_f32_16x16x32_bf16 v[96:99], v[16:19], v[184:187], 0
	v_mfma_f32_16x16x32_bf16 v[100:103], v[24:27], v[192:195], 0
	v_mfma_f32_16x16x32_bf16 v[104:107], v[32:35], v[200:203], 0
	v_mfma_f32_16x16x32_bf16 v[96:99], v[20:23], v[188:191], v[96:99]
	v_mfma_f32_16x16x32_bf16 v[100:103], v[28:31], v[196:199], v[100:103]
	v_mfma_f32_16x16x32_bf16 v[104:107], v[36:39], v[204:207], v[104:107]
	v_mfma_f32_16x16x32_bf16 v[104:107], v[40:43], v[208:211], v[104:107]
	v_mfma_f32_16x16x32_bf16 v[104:107], v[44:47], v[212:215], v[104:107]
	v_add_u32_e32 v132, 0x800, v132
	v_add_u32_e32 v133, 0x1000, v133
	v_add_u32_e32 v134, 64, v134
	s_nop 4
	v_add_f32_e32 v108, v48, v96
	v_add_f32_e32 v109, v49, v97
	v_add_f32_e32 v110, v50, v98
	v_add_f32_e32 v111, v51, v99
	v_add_f32_e32 v112, v52, v100
	v_add_f32_e32 v113, v53, v101
	v_add_f32_e32 v114, v54, v102
	v_add_f32_e32 v115, v55, v103
	v_mul_f32_e32 v108, 0xbfb8aa3b, v108
	v_mul_f32_e32 v109, 0xbfb8aa3b, v109
	v_mul_f32_e32 v110, 0xbfb8aa3b, v110
	v_mul_f32_e32 v111, 0xbfb8aa3b, v111
	v_mul_f32_e32 v112, 0xbfb8aa3b, v112
	v_mul_f32_e32 v113, 0xbfb8aa3b, v113
	v_mul_f32_e32 v114, 0xbfb8aa3b, v114
	v_mul_f32_e32 v115, 0xbfb8aa3b, v115
	v_exp_f32_e32 v108, v108
	v_exp_f32_e32 v109, v109
	v_exp_f32_e32 v110, v110
	v_exp_f32_e32 v111, v111
	v_exp_f32_e32 v112, v112
	v_exp_f32_e32 v113, v113
	v_exp_f32_e32 v114, v114
	v_exp_f32_e32 v115, v115
	v_add_f32_e32 v108, 1.0, v108
	v_add_f32_e32 v109, 1.0, v109
	v_add_f32_e32 v110, 1.0, v110
	v_add_f32_e32 v111, 1.0, v111
	v_add_f32_e32 v112, 1.0, v112
	v_add_f32_e32 v113, 1.0, v113
	v_add_f32_e32 v114, 1.0, v114
	v_add_f32_e32 v115, 1.0, v115
	v_rcp_f32_e32 v108, v108
	v_rcp_f32_e32 v109, v109
	v_rcp_f32_e32 v110, v110
	v_rcp_f32_e32 v111, v111
	v_rcp_f32_e32 v112, v112
	v_rcp_f32_e32 v113, v113
	v_rcp_f32_e32 v114, v114
	v_rcp_f32_e32 v115, v115
	v_mul_f32_e32 v108, 0xbf60028b, v108
	v_mul_f32_e32 v109, 0xbf60028b, v109
	v_mul_f32_e32 v110, 0xbf60028b, v110
	v_mul_f32_e32 v111, 0xbf60028b, v111
	v_cvt_pk_bf16_f32 v116, v112, v113
	v_cvt_pk_bf16_f32 v117, v114, v115
	v_exp_f32_e32 v108, v108
	v_exp_f32_e32 v109, v109
	v_exp_f32_e32 v110, v110
	v_exp_f32_e32 v111, v111
	v_cvt_pk_bf16_f32 v118, v104, v105
	v_cvt_pk_bf16_f32 v119, v106, v107
	global_store_dwordx2 v136, v[116:117], s[44:45]
	global_store_dwordx2 v136, v[118:119], s[46:47]
	global_store_dwordx4 v135, v[108:111], s[54:55]
	v_add_u32_e32 v136, 32, v136
	v_add_u32_e32 v135, 64, v135
	s_branch .Llora_done
